# attention LDS-DMA: counted waits (vmcnt(8) before the first key tile's QK, vmcnt(0) before the second tile's first read)
# speedup vs baseline: 1.0100x; 1.0100x over previous
.Latt_noissue:
	s_waitcnt vmcnt(8)
	s_waitcnt lgkmcnt(7)
	v_cmp_lt_i32_e32 vcc, -1, v164
	s_waitcnt lgkmcnt(0)
	ds_read_b128 v[228:231], v88
	ds_read_b128 v[232:235], v89
	ds_read_b128 v[236:239], v90
	ds_read_b128 v[240:243], v91
	s_waitcnt lgkmcnt(3)
	v_mfma_f32_16x16x32_bf16 v[134:137], v[228:231], v[196:199], 0
	ds_read_b128 v[228:231], v88 offset:256
	s_waitcnt lgkmcnt(3)
	v_mfma_f32_16x16x32_bf16 v[134:137], v[232:235], v[200:203], v[134:137]
	ds_read_b128 v[232:235], v89 offset:256
	s_waitcnt lgkmcnt(3)
	v_mfma_f32_16x16x32_bf16 v[134:137], v[236:239], v[204:207], v[134:137]
	ds_read_b128 v[236:239], v90 offset:256
	s_waitcnt lgkmcnt(3)
	v_mfma_f32_16x16x32_bf16 v[134:137], v[240:243], v[208:211], v[134:137]
	ds_read_b128 v[240:243], v91 offset:256
	s_waitcnt lgkmcnt(3)
	v_mfma_f32_16x16x32_bf16 v[134:137], v[228:231], v[212:215], v[134:137]
	s_waitcnt vmcnt(0)
	ds_read_b128 v[228:231], v88 offset:8192
	s_waitcnt lgkmcnt(3)
	v_mfma_f32_16x16x32_bf16 v[134:137], v[232:235], v[216:219], v[134:137]
	ds_read_b128 v[232:235], v89 offset:8192
	s_waitcnt lgkmcnt(3)
	v_mfma_f32_16x16x32_bf16 v[134:137], v[236:239], v[220:223], v[134:137]
	ds_read_b128 v[236:239], v90 offset:8192
	s_waitcnt lgkmcnt(3)
	v_mfma_f32_16x16x32_bf16 v[134:137], v[240:243], v[224:227], v[134:137]
	ds_read_b128 v[240:243], v91 offset:8192
	s_waitcnt lgkmcnt(3)
	v_mfma_f32_16x16x32_bf16 v[72:75], v[228:231], v[196:199], 0
	ds_read_b128 v[228:231], v88 offset:8448
	s_waitcnt lgkmcnt(3)
	v_mfma_f32_16x16x32_bf16 v[72:75], v[232:235], v[200:203], v[72:75]
	ds_read_b128 v[232:235], v89 offset:8448
	s_waitcnt lgkmcnt(3)
	v_mfma_f32_16x16x32_bf16 v[72:75], v[236:239], v[204:207], v[72:75]
	ds_read_b128 v[236:239], v90 offset:8448
	s_waitcnt lgkmcnt(3)
	v_mfma_f32_16x16x32_bf16 v[72:75], v[240:243], v[208:211], v[72:75]
	ds_read_b128 v[240:243], v91 offset:8448
	v_subrev_u32_e32 v80, s29, v170
	v_med3_i32 v80, v80, s4, v189
	v_lshl_add_u32 v80, v80, 6, v116
	ds_read_b32 v80, v80 offset:8192
	s_waitcnt lgkmcnt(4)
	v_mfma_f32_16x16x32_bf16 v[72:75], v[228:231], v[212:215], v[72:75]
	s_waitcnt lgkmcnt(3)
	v_mfma_f32_16x16x32_bf16 v[72:75], v[232:235], v[216:219], v[72:75]
	s_waitcnt lgkmcnt(2)
	v_mfma_f32_16x16x32_bf16 v[72:75], v[236:239], v[220:223], v[72:75]
	s_waitcnt lgkmcnt(1)
	v_mfma_f32_16x16x32_bf16 v[72:75], v[240:243], v[224:227], v[72:75]
	v_subrev_u32_e32 v76, s29, v164
	v_med3_i32 v76, v76, s4, v189
	v_subrev_u32_e32 v77, s29, v166
	v_lshl_add_u32 v76, v76, 6, v116
	v_med3_i32 v77, v77, s4, v189
	v_subrev_u32_e32 v78, s29, v168
	ds_read_b32 v76, v76 offset:8192
	v_lshl_add_u32 v77, v77, 6, v116
	v_med3_i32 v78, v78, s4, v189
	v_subrev_u32_e32 v79, s29, v169
	ds_read_b32 v77, v77 offset:8192
	v_lshl_add_u32 v78, v78, 6, v116
	v_med3_i32 v79, v79, s4, v189
	ds_read_b32 v78, v78 offset:8192
	v_lshl_add_u32 v79, v79, 6, v116
	ds_read_b32 v79, v79 offset:8192
	s_waitcnt lgkmcnt(3)
	v_fmac_f32_e32 v76, 0x3d800000, v134
	v_cndmask_b32_e32 v76, v190, v76, vcc
	s_waitcnt lgkmcnt(2)
	v_fmac_f32_e32 v77, 0x3d800000, v135
	v_cmp_lt_i32_e32 vcc, -1, v166
	s_waitcnt lgkmcnt(1)
	v_fmac_f32_e32 v78, 0x3d800000, v136
	s_waitcnt lgkmcnt(0)
	v_fmac_f32_e32 v79, 0x3d800000, v137
	v_cndmask_b32_e32 v77, v190, v77, vcc
	v_cmp_lt_i32_e32 vcc, -1, v168
	v_fmac_f32_e32 v80, 0x3d800000, v72
	s_nop 0
	v_cndmask_b32_e32 v78, v190, v78, vcc
	v_cmp_lt_i32_e32 vcc, -1, v169
	s_nop 1
	v_cndmask_b32_e32 v79, v190, v79, vcc
	v_cmp_lt_i32_e32 vcc, -1, v170
	v_max_f32_e32 v81, v78, v79
	s_nop 0
	v_cndmask_b32_e32 v72, v190, v80, vcc
	v_subrev_u32_e32 v80, s29, v176
	v_med3_i32 v80, v80, s4, v189
	v_lshl_add_u32 v80, v80, 6, v116
	ds_read_b32 v80, v80 offset:8192
	v_cmp_lt_i32_e32 vcc, -1, v176
	s_waitcnt lgkmcnt(0)
	v_fmac_f32_e32 v80, 0x3d800000, v73
	v_subrev_u32_e32 v73, s29, v177
	v_med3_i32 v73, v73, s4, v189
	v_lshl_add_u32 v73, v73, 6, v116
	ds_read_b32 v73, v73 offset:8192
	v_cndmask_b32_e32 v80, v190, v80, vcc
	v_cmp_lt_i32_e32 vcc, -1, v177
	s_waitcnt lgkmcnt(0)
	v_fmac_f32_e32 v73, 0x3d800000, v74
	v_cndmask_b32_e32 v74, v190, v73, vcc
	v_subrev_u32_e32 v73, s29, v191
	v_med3_i32 v73, v73, s4, v189
	v_lshl_add_u32 v73, v73, 6, v116
	ds_read_b32 v73, v73 offset:8192
	v_cmp_lt_i32_e32 vcc, -1, v191
	s_waitcnt lgkmcnt(0)
	v_fmac_f32_e32 v73, 0x3d800000, v75
	v_cndmask_b32_e32 v75, v190, v73, vcc
	s_add_i32 s2, s30, 1
	s_cmp_eq_u32 s2, 8
	s_cbranch_scc1 .Latt_qpf
	s_lshr_b32 s3, s2, 1
	s_cmp_eq_u32 s3, 2
	s_cselect_b64 vcc, -1, 0
	v_cndmask_b32_e32 v244, v127, v126, vcc
	s_cmp_eq_u32 s3, 1
	s_cselect_b64 vcc, -1, 0
	v_cndmask_b32_e32 v244, v244, v125, vcc
	s_cmp_eq_u32 s3, 0
	s_cselect_b64 vcc, -1, 0
	v_cndmask_b32_e32 v244, v244, v124, vcc
	s_bitcmp1_b32 s2, 0
	s_cbranch_scc1 .Latt_a_odd
	v_readlane_b32 s0, v244, 0
	v_readlane_b32 s1, v244, 1
	v_readlane_b32 vcc_lo, v244, 2
	v_readlane_b32 vcc_hi, v244, 3
	s_mov_b32 exec_lo, 0xffff
	s_mov_b32 exec_hi, 0x0
	v_mov_b32_e32 v164, s0
	v_mov_b32_e32 v166, s1
	v_mov_b32_e32 v168, vcc_lo
	v_mov_b32_e32 v169, vcc_hi
	s_mov_b64 exec, -1
	s_max_i32 s0, s0, 0
	s_max_i32 s1, s1, 0
	s_max_i32 vcc_lo, vcc_lo, 0
	s_max_i32 vcc_hi, vcc_hi, 0
	s_sub_i32 s1, s1, s0
	s_sub_i32 vcc_hi, vcc_hi, vcc_lo
	s_lshl_b32 s0, s0, 9
	s_lshl_b32 s1, s1, 9
	s_lshl_b32 vcc_lo, vcc_lo, 9
	s_lshl_b32 vcc_hi, vcc_hi, 9
	v_add_u32_e32 v156, s0, v152
	v_add_u32_e32 v157, vcc_lo, v153
	v_mad_i32_i24 v156, v115, s1, v156
	v_mad_i32_i24 v157, v115, vcc_hi, v157
	v_readlane_b32 s0, v244, 4
	v_readlane_b32 s1, v244, 5
	v_readlane_b32 vcc_lo, v244, 6
	v_readlane_b32 vcc_hi, v244, 7
	s_mov_b32 exec_lo, 0xffff0000
	s_mov_b32 exec_hi, 0x0
	v_mov_b32_e32 v164, s0
	v_mov_b32_e32 v166, s1
	v_mov_b32_e32 v168, vcc_lo
	v_mov_b32_e32 v169, vcc_hi
	s_mov_b64 exec, -1
	s_max_i32 s0, s0, 0
	s_max_i32 s1, s1, 0
	s_max_i32 vcc_lo, vcc_lo, 0
	s_max_i32 vcc_hi, vcc_hi, 0
	s_sub_i32 s1, s1, s0
	s_sub_i32 vcc_hi, vcc_hi, vcc_lo
	s_lshl_b32 s0, s0, 9
	s_lshl_b32 s1, s1, 9
	s_lshl_b32 vcc_lo, vcc_lo, 9
	s_lshl_b32 vcc_hi, vcc_hi, 9
	v_add_u32_e32 v158, s0, v154
	v_add_u32_e32 v159, vcc_lo, v155
	v_mad_i32_i24 v158, v115, s1, v158
	v_mad_i32_i24 v159, v115, vcc_hi, v159
	v_readlane_b32 s0, v244, 8
	v_readlane_b32 s1, v244, 9
	v_readlane_b32 vcc_lo, v244, 10
	v_readlane_b32 vcc_hi, v244, 11
	s_mov_b32 exec_lo, 0x0
	s_mov_b32 exec_hi, 0xffff
	v_mov_b32_e32 v164, s0
	v_mov_b32_e32 v166, s1
	v_mov_b32_e32 v168, vcc_lo
	v_mov_b32_e32 v169, vcc_hi
	s_mov_b64 exec, -1
	s_max_i32 s0, s0, 0
	s_max_i32 s1, s1, 0
	s_max_i32 vcc_lo, vcc_lo, 0
	s_max_i32 vcc_hi, vcc_hi, 0
	s_sub_i32 s1, s1, s0
	s_sub_i32 vcc_hi, vcc_hi, vcc_lo
	s_lshl_b32 s0, s0, 9
	s_lshl_b32 s1, s1, 9
	s_lshl_b32 vcc_lo, vcc_lo, 9
	s_lshl_b32 vcc_hi, vcc_hi, 9
	v_add_u32_e32 v160, s0, v152
	v_add_u32_e32 v161, vcc_lo, v153
	v_mad_i32_i24 v160, v115, s1, v160
	v_mad_i32_i24 v161, v115, vcc_hi, v161
	v_readlane_b32 s0, v244, 12
	v_readlane_b32 s1, v244, 13
	v_readlane_b32 vcc_lo, v244, 14
	v_readlane_b32 vcc_hi, v244, 15
	s_mov_b32 exec_lo, 0x0
	s_mov_b32 exec_hi, 0xffff0000
	v_mov_b32_e32 v164, s0
	v_mov_b32_e32 v166, s1
	v_mov_b32_e32 v168, vcc_lo
	v_mov_b32_e32 v169, vcc_hi
	s_mov_b64 exec, -1
	s_max_i32 s0, s0, 0
	s_max_i32 s1, s1, 0
	s_max_i32 vcc_lo, vcc_lo, 0
	s_max_i32 vcc_hi, vcc_hi, 0
	s_sub_i32 s1, s1, s0
	s_sub_i32 vcc_hi, vcc_hi, vcc_lo
	s_lshl_b32 s0, s0, 9
	s_lshl_b32 s1, s1, 9
	s_lshl_b32 vcc_lo, vcc_lo, 9
	s_lshl_b32 vcc_hi, vcc_hi, 9
	v_add_u32_e32 v162, s0, v154
	v_add_u32_e32 v163, vcc_lo, v155
	v_mad_i32_i24 v162, v115, s1, v162
	v_mad_i32_i24 v163, v115, vcc_hi, v163
	v_readlane_b32 s0, v244, 16
	v_readlane_b32 s1, v244, 17
	v_readlane_b32 vcc_lo, v244, 18
	v_readlane_b32 vcc_hi, v244, 19
	s_mov_b32 exec_lo, 0xffff
	s_mov_b32 exec_hi, 0x0
	v_mov_b32_e32 v170, s0
	v_mov_b32_e32 v176, s1
	v_mov_b32_e32 v177, vcc_lo
	v_mov_b32_e32 v191, vcc_hi
	s_mov_b64 exec, -1
	s_max_i32 s0, s0, 0
	s_max_i32 s1, s1, 0
	s_max_i32 vcc_lo, vcc_lo, 0
	s_max_i32 vcc_hi, vcc_hi, 0
	s_sub_i32 s1, s1, s0
	s_sub_i32 vcc_hi, vcc_hi, vcc_lo
	s_lshl_b32 s0, s0, 9
	s_lshl_b32 s1, s1, 9
	s_lshl_b32 vcc_lo, vcc_lo, 9
	s_lshl_b32 vcc_hi, vcc_hi, 9
	v_add_u32_e32 v144, s0, v152
	v_add_u32_e32 v145, vcc_lo, v153
	v_mad_i32_i24 v144, v115, s1, v144
	v_mad_i32_i24 v145, v115, vcc_hi, v145
	v_readlane_b32 s0, v244, 20
	v_readlane_b32 s1, v244, 21
	v_readlane_b32 vcc_lo, v244, 22
	v_readlane_b32 vcc_hi, v244, 23
	s_mov_b32 exec_lo, 0xffff0000
	s_mov_b32 exec_hi, 0x0
	v_mov_b32_e32 v170, s0
	v_mov_b32_e32 v176, s1
	v_mov_b32_e32 v177, vcc_lo
	v_mov_b32_e32 v191, vcc_hi
	s_mov_b64 exec, -1
	s_max_i32 s0, s0, 0
	s_max_i32 s1, s1, 0
	s_max_i32 vcc_lo, vcc_lo, 0
	s_max_i32 vcc_hi, vcc_hi, 0
	s_sub_i32 s1, s1, s0
	s_sub_i32 vcc_hi, vcc_hi, vcc_lo
	s_lshl_b32 s0, s0, 9
	s_lshl_b32 s1, s1, 9
	s_lshl_b32 vcc_lo, vcc_lo, 9
	s_lshl_b32 vcc_hi, vcc_hi, 9
	v_add_u32_e32 v146, s0, v154
	v_add_u32_e32 v147, vcc_lo, v155
	v_mad_i32_i24 v146, v115, s1, v146
	v_mad_i32_i24 v147, v115, vcc_hi, v147
	v_readlane_b32 s0, v244, 24
	v_readlane_b32 s1, v244, 25
	v_readlane_b32 vcc_lo, v244, 26
	v_readlane_b32 vcc_hi, v244, 27
	s_mov_b32 exec_lo, 0x0
	s_mov_b32 exec_hi, 0xffff
	v_mov_b32_e32 v170, s0
	v_mov_b32_e32 v176, s1
	v_mov_b32_e32 v177, vcc_lo
	v_mov_b32_e32 v191, vcc_hi
	s_mov_b64 exec, -1
	s_max_i32 s0, s0, 0
	s_max_i32 s1, s1, 0
	s_max_i32 vcc_lo, vcc_lo, 0
	s_max_i32 vcc_hi, vcc_hi, 0
	s_sub_i32 s1, s1, s0
	s_sub_i32 vcc_hi, vcc_hi, vcc_lo
	s_lshl_b32 s0, s0, 9
	s_lshl_b32 s1, s1, 9
	s_lshl_b32 vcc_lo, vcc_lo, 9
	s_lshl_b32 vcc_hi, vcc_hi, 9
	v_add_u32_e32 v172, s0, v152
	v_add_u32_e32 v173, vcc_lo, v153
	v_mad_i32_i24 v172, v115, s1, v172
	v_mad_i32_i24 v173, v115, vcc_hi, v173
	v_readlane_b32 s0, v244, 28
	v_readlane_b32 s1, v244, 29
	v_readlane_b32 vcc_lo, v244, 30
	v_readlane_b32 vcc_hi, v244, 31
	s_mov_b32 exec_lo, 0x0
	s_mov_b32 exec_hi, 0xffff0000
	v_mov_b32_e32 v170, s0
	v_mov_b32_e32 v176, s1
	v_mov_b32_e32 v177, vcc_lo
	v_mov_b32_e32 v191, vcc_hi
	s_mov_b64 exec, -1
	s_max_i32 s0, s0, 0
	s_max_i32 s1, s1, 0
	s_max_i32 vcc_lo, vcc_lo, 0
	s_max_i32 vcc_hi, vcc_hi, 0
	s_sub_i32 s1, s1, s0
	s_sub_i32 vcc_hi, vcc_hi, vcc_lo
	s_lshl_b32 s0, s0, 9
	s_lshl_b32 s1, s1, 9
	s_lshl_b32 vcc_lo, vcc_lo, 9
	s_lshl_b32 vcc_hi, vcc_hi, 9
	v_add_u32_e32 v174, s0, v154
	v_add_u32_e32 v175, vcc_lo, v155
	v_mad_i32_i24 v174, v115, s1, v174
	v_mad_i32_i24 v175, v115, vcc_hi, v175
	s_branch .Latt_a_done
